# phase 2 load balance: third conv tiles on workgroups 320..447 instead of 64..191
# baseline (speedup 1.0000x reference)
; DEVI void phase2(const Params& p, unsigned char* smem) {
;   u16* sA = (u16*)smem; u16* sB = sA + 128 * 72;
; #pragma unroll 1
;   for (int tile = blockIdx.x; tile < 64 + 1024; tile += gridDim.x) {
.LBB0_552:
	s_load_dword s0, s[6:7], 0x0
	s_waitcnt lgkmcnt(0)
	s_add_i32 s35, s0, s35
	s_cmp_lg_u32 s0, 0x200
	s_cbranch_scc1 .Lp2_latch_plain
	s_cmp_lg_u32 s96, 0
	s_cbranch_scc1 .LBB0_694
	s_cmp_lt_u32 s90, 64
	s_cbranch_scc1 .LBB0_694
	s_add_u32 s1, s90, 0x400
	s_cmp_lg_u32 s35, s1
	s_cbranch_scc1 .Lp2_latch_plain
	s_sub_u32 s1, s90, 0x140
	s_cmp_ge_u32 s1, 0x80
	s_cbranch_scc1 .Lp2_latch_plain
	s_mov_b32 s96, 1
	s_movk_i32 s1, 0x380
	s_cmp_lt_u32 s90, 0x180
	s_cselect_b32 s1, 0x140, s1
	s_sub_u32 s35, s35, s1
